# v27 plus m3: per value-half the 8 staging loads are issued together (was 6 dependent round trips) and the second half's loads are prefetched over the first half's MFMA section
# speedup vs baseline: 1.0100x; 1.0029x over previous
.LBB0_576:
	s_waitcnt lgkmcnt(14)
	v_mul_f32_e32 v5, v5, v57
	v_fmac_f32_e32 v5, v4, v56
	v_mul_f32_e32 v4, v7, v59
	v_fmac_f32_e32 v4, v6, v58
	v_mul_f32_e32 v1, v1, v61
	v_add_f32_e32 v4, v5, v4
	v_fmac_f32_e32 v1, v0, v60
	v_add_f32_e32 v0, v4, v1
	v_mul_f32_e32 v1, v3, v63
	v_fmac_f32_e32 v1, v2, v62
	v_add_f32_e32 v0, v0, v1
	v_mul_f32_e32 v1, v13, v115
	v_mul_f32_e32 v2, v15, v117
	v_fmac_f32_e32 v1, v12, v114
	v_fmac_f32_e32 v2, v14, v116
	v_add_f32_e32 v1, v1, v2
	v_mul_f32_e32 v2, v9, v119
	v_fmac_f32_e32 v2, v8, v118
	v_add_f32_e32 v1, v1, v2
	v_mul_f32_e32 v2, v11, v121
	v_fmac_f32_e32 v2, v10, v120
	v_add_f32_e32 v1, v1, v2
	s_waitcnt lgkmcnt(12)
	v_mul_f32_e32 v2, v37, v123
	v_mul_f32_e32 v3, v39, v125
	v_fmac_f32_e32 v2, v36, v122
	v_fmac_f32_e32 v3, v38, v124
	v_add_f32_e32 v2, v2, v3
	s_waitcnt lgkmcnt(11)
	v_mul_f32_e32 v3, v33, v127
	v_fmac_f32_e32 v3, v32, v126
	v_add_f32_e32 v2, v2, v3
	v_mul_f32_e32 v3, v35, v129
	v_fmac_f32_e32 v3, v34, v128
	v_add_f32_e32 v2, v2, v3
	s_waitcnt lgkmcnt(9)
	v_mul_f32_e32 v3, v45, v131
	v_mul_f32_e32 v4, v47, v133
	v_fmac_f32_e32 v3, v44, v130
	v_fmac_f32_e32 v4, v46, v132
	v_add_f32_e32 v3, v3, v4
	s_waitcnt lgkmcnt(8)
	v_mul_f32_e32 v4, v41, v135
	v_fmac_f32_e32 v4, v40, v134
	v_add_f32_e32 v3, v3, v4
	v_mul_f32_e32 v4, v43, v139
	v_add_f32_e32 v0, 0, v0
	v_fmac_f32_e32 v4, v42, v138
	v_add_f32_e32 v0, v0, v1
	v_add_f32_e32 v3, v3, v4
	v_add_f32_e32 v0, v0, v2
	v_add_f32_e32 v137, v0, v3
	ds_bpermute_b32 v0, v160, v136
	ds_bpermute_b32 v1, v160, v137
	s_mul_i32 s20, s49, 0x1800
	ds_write_b64 v164, v[48:49] offset:224
	s_waitcnt lgkmcnt(0)
	s_barrier
	v_pk_add_f32 v[0:1], v[136:137], v[0:1]
	ds_bpermute_b32 v2, v154, v0
	ds_bpermute_b32 v3, v154, v1
	s_waitcnt lgkmcnt(0)
	v_add_u32_e32 v49, 0x400, v198
	v_add_u32_e32 v50, 0x800, v198
	v_add_u32_e32 v51, 0xc00, v198
	v_pk_add_f32 v[0:1], v[0:1], v[2:3]
	v_or_b32_e32 v2, s48, v72
	v_fmac_f32_e32 v0, v54, v1
	v_add_f32_e32 v1, v52, v53
	v_mul_f32_e32 v1, 0xbfb8aa3b, v1
	v_exp_f32_e32 v1, v1
	v_add_u32_e32 v52, 0x400, v199
	v_add_u32_e32 v53, 0x800, v199
	v_add_u32_e32 v54, 0xc00, v199
	v_max_f32_e64 v107, |v0|, v1
	v_mov_b64_e32 v[0:1], s[88:89]
	v_mad_u64_u32 v[0:1], s[48:49], v2, s53, v[0:1]
	v_add_u32_e32 v1, s20, v1
	s_lshl_b32 s20, s58, 9
	v_lshl_add_u64 v[8:9], v[0:1], 0, s[20:21]
	v_lshl_add_u64 v[32:33], v[82:83], 1, v[8:9]
	v_add_co_u32_e32 v34, vcc, s55, v32
	global_load_dwordx4 v[206:209], v[32:33], off offset:2048
	s_nop 0
	v_addc_co_u32_e32 v35, vcc, 0, v33, vcc
	global_load_dwordx4 v[210:213], v[34:35], off
	v_lshl_add_u64 v[36:37], v[84:85], 1, v[8:9]
	v_add_co_u32_e32 v38, vcc, s55, v36
	v_lshl_add_u64 v[40:41], s[94:95], 0, v[104:105]
	s_nop 0
	v_addc_co_u32_e32 v39, vcc, 0, v37, vcc
	v_lshl_add_u64 v[42:43], s[94:95], 0, v[102:103]
	v_lshl_add_u64 v[44:45], s[94:95], 0, v[100:101]
	v_lshl_add_u64 v[46:47], s[94:95], 0, v[98:99]
	v_add_u32_e32 v48, v164, v70
	v_div_scale_f32 v109, s[48:49], v107, v107, 1.0
	s_mov_b32 s48, 0x800000
	s_add_i32 s4, s4, s90
	v_lshl_add_u64 v[96:97], v[96:97], 0, s[42:43]
	v_lshl_add_u64 v[98:99], v[98:99], 0, s[44:45]
	v_lshl_add_u64 v[100:101], v[100:101], 0, s[44:45]
	v_lshl_add_u64 v[102:103], v[102:103], 0, s[44:45]
	v_lshl_add_u64 v[104:105], v[104:105], 0, s[44:45]
	s_mov_b32 s98, s56
	s_mov_b32 s99, 0
	global_load_dwordx4 v[214:217], v[36:37], off offset:2048
	global_load_dwordx4 v[218:221], v[38:39], off
	v_lshl_add_u64 v[242:243], v[40:41], 0, s[98:99]
	v_lshl_add_u64 v[244:245], v[42:43], 0, s[98:99]
	v_lshl_add_u64 v[246:247], v[44:45], 0, s[98:99]
	v_lshl_add_u64 v[248:249], v[46:47], 0, s[98:99]
	global_load_dwordx4 v[222:225], v[242:243], off
	global_load_dwordx4 v[230:233], v[244:245], off
	global_load_dwordx4 v[234:237], v[246:247], off
	global_load_dwordx4 v[238:241], v[248:249], off
	s_waitcnt vmcnt(6)
	v_and_b32_e32 v250, 0xffff, v206
	v_lshrrev_b32_e32 v251, 16, v206
	v_lshl_or_b32 v250, v210, 16, v250
	v_and_or_b32 v251, v210, s54, v251
	ds_write2_b32 v198, v250, v251 offset1:132
	v_and_b32_e32 v250, 0xffff, v207
	v_lshrrev_b32_e32 v251, 16, v207
	v_lshl_or_b32 v250, v211, 16, v250
	v_and_or_b32 v251, v211, s54, v251
	ds_write2_b32 v49, v250, v251 offset0:8 offset1:140
	v_and_b32_e32 v250, 0xffff, v208
	v_lshrrev_b32_e32 v251, 16, v208
	v_lshl_or_b32 v250, v212, 16, v250
	v_and_or_b32 v251, v212, s54, v251
	ds_write2_b32 v50, v250, v251 offset0:16 offset1:148
	v_and_b32_e32 v250, 0xffff, v209
	v_lshrrev_b32_e32 v251, 16, v209
	v_lshl_or_b32 v250, v213, 16, v250
	v_and_or_b32 v251, v213, s54, v251
	ds_write2_b32 v51, v250, v251 offset0:24 offset1:156
	s_waitcnt vmcnt(4)
	v_and_b32_e32 v250, 0xffff, v214
	v_lshrrev_b32_e32 v251, 16, v214
	v_lshl_or_b32 v250, v218, 16, v250
	v_and_or_b32 v251, v218, s54, v251
	ds_write2_b32 v199, v250, v251 offset1:132
	v_and_b32_e32 v250, 0xffff, v215
	v_lshrrev_b32_e32 v251, 16, v215
	v_lshl_or_b32 v250, v219, 16, v250
	v_and_or_b32 v251, v219, s54, v251
	ds_write2_b32 v52, v250, v251 offset0:8 offset1:140
	v_and_b32_e32 v250, 0xffff, v216
	v_lshrrev_b32_e32 v251, 16, v216
	v_lshl_or_b32 v250, v220, 16, v250
	v_and_or_b32 v251, v220, s54, v251
	ds_write2_b32 v53, v250, v251 offset0:16 offset1:148
	v_and_b32_e32 v250, 0xffff, v217
	v_lshrrev_b32_e32 v251, 16, v217
	v_lshl_or_b32 v250, v221, 16, v250
	v_and_or_b32 v251, v221, s54, v251
	ds_write2_b32 v54, v250, v251 offset0:24 offset1:156
	s_waitcnt vmcnt(3)
	ds_write_b128 v86, v[222:225] offset:256
	s_waitcnt vmcnt(2)
	ds_write_b128 v88, v[230:233] offset:256
	s_waitcnt vmcnt(1)
	ds_write_b128 v90, v[234:237] offset:256
	s_waitcnt vmcnt(0)
	ds_write_b128 v92, v[238:241] offset:256
	s_waitcnt lgkmcnt(0)
	s_barrier
	s_mov_b32 s98, s57
	s_mov_b32 s99, 0
	global_load_dwordx4 v[206:209], v[32:33], off offset:2304
	global_load_dwordx4 v[210:213], v[34:35], off offset:256
	global_load_dwordx4 v[214:217], v[36:37], off offset:2304
	global_load_dwordx4 v[218:221], v[38:39], off offset:256
	v_lshl_add_u64 v[242:243], v[40:41], 0, s[98:99]
	v_lshl_add_u64 v[244:245], v[42:43], 0, s[98:99]
	v_lshl_add_u64 v[246:247], v[44:45], 0, s[98:99]
	v_lshl_add_u64 v[248:249], v[46:47], 0, s[98:99]
	global_load_dwordx4 v[222:225], v[242:243], off
	global_load_dwordx4 v[230:233], v[244:245], off
	global_load_dwordx4 v[234:237], v[246:247], off
	global_load_dwordx4 v[238:241], v[248:249], off
	ds_read_b128 v[0:3], v48
	ds_read_b128 v[4:7], v196
	ds_read_b128 v[8:11], v196 offset:8448
	ds_read_b128 v[28:31], v196 offset:50688
	ds_read_b128 v[12:15], v196 offset:16896
	ds_read_b128 v[16:19], v196 offset:25344
	ds_read_b128 v[20:23], v196 offset:33792
	ds_read_b128 v[24:27], v196 offset:42240
	ds_read_b128 v[56:59], v200
	s_waitcnt lgkmcnt(7)
	v_mfma_f32_16x16x32_bf16 v[4:7], v[4:7], v[0:3], 0
	s_waitcnt lgkmcnt(6)
	v_mfma_f32_16x16x32_bf16 v[8:11], v[8:11], v[0:3], 0
	s_waitcnt lgkmcnt(4)
	v_mfma_f32_16x16x32_bf16 v[12:15], v[12:15], v[0:3], 0
	s_waitcnt lgkmcnt(3)
	v_mfma_f32_16x16x32_bf16 v[16:19], v[16:19], v[0:3], 0
	s_waitcnt lgkmcnt(2)
	v_mfma_f32_16x16x32_bf16 v[20:23], v[20:23], v[0:3], 0
	s_waitcnt lgkmcnt(1)
	v_mfma_f32_16x16x32_bf16 v[24:27], v[24:27], v[0:3], 0
	v_mfma_f32_16x16x32_bf16 v[28:31], v[28:31], v[0:3], 0
	s_waitcnt lgkmcnt(0)
	v_mfma_f32_16x16x32_bf16 v[0:3], v[56:59], v[0:3], 0
	ds_read_b128 v[56:59], v48 offset:64
	ds_read_b128 v[60:63], v196 offset:64
	s_waitcnt lgkmcnt(0)
	v_mfma_f32_16x16x32_bf16 v[4:7], v[60:63], v[56:59], v[4:7]
	ds_read_b128 v[60:63], v196 offset:8512
	s_waitcnt lgkmcnt(0)
	v_mfma_f32_16x16x32_bf16 v[8:11], v[60:63], v[56:59], v[8:11]
	ds_read_b128 v[60:63], v196 offset:16960
	s_waitcnt lgkmcnt(0)
	v_mfma_f32_16x16x32_bf16 v[12:15], v[60:63], v[56:59], v[12:15]
	ds_read_b128 v[60:63], v196 offset:25408
	s_waitcnt lgkmcnt(0)
	v_mfma_f32_16x16x32_bf16 v[16:19], v[60:63], v[56:59], v[16:19]
	ds_read_b128 v[60:63], v196 offset:33856
	s_waitcnt lgkmcnt(0)
	v_mfma_f32_16x16x32_bf16 v[20:23], v[60:63], v[56:59], v[20:23]
	ds_read_b128 v[60:63], v196 offset:42304
	s_waitcnt lgkmcnt(0)
	v_mfma_f32_16x16x32_bf16 v[24:27], v[60:63], v[56:59], v[24:27]
	ds_read_b128 v[60:63], v196 offset:50752
	s_waitcnt lgkmcnt(0)
	v_mfma_f32_16x16x32_bf16 v[28:31], v[60:63], v[56:59], v[28:31]
	ds_read_b128 v[60:63], v200 offset:64
	s_waitcnt lgkmcnt(0)
	v_mfma_f32_16x16x32_bf16 v[0:3], v[60:63], v[56:59], v[0:3]
	ds_read_b128 v[56:59], v48 offset:128
	ds_read_b128 v[60:63], v196 offset:128
	s_waitcnt lgkmcnt(0)
	v_mfma_f32_16x16x32_bf16 v[4:7], v[60:63], v[56:59], v[4:7]
	ds_read_b128 v[60:63], v196 offset:8576
	s_waitcnt lgkmcnt(0)
	v_mfma_f32_16x16x32_bf16 v[8:11], v[60:63], v[56:59], v[8:11]
	ds_read_b128 v[60:63], v196 offset:17024
	s_waitcnt lgkmcnt(0)
	v_mfma_f32_16x16x32_bf16 v[12:15], v[60:63], v[56:59], v[12:15]
	ds_read_b128 v[60:63], v196 offset:25472
	s_waitcnt lgkmcnt(0)
	v_mfma_f32_16x16x32_bf16 v[16:19], v[60:63], v[56:59], v[16:19]
	ds_read_b128 v[60:63], v196 offset:33920
	s_waitcnt lgkmcnt(0)
	v_mfma_f32_16x16x32_bf16 v[20:23], v[60:63], v[56:59], v[20:23]
	ds_read_b128 v[60:63], v196 offset:42368
	s_waitcnt lgkmcnt(0)
	v_mfma_f32_16x16x32_bf16 v[24:27], v[60:63], v[56:59], v[24:27]
	ds_read_b128 v[60:63], v196 offset:50816
	s_waitcnt lgkmcnt(0)
	v_mfma_f32_16x16x32_bf16 v[28:31], v[60:63], v[56:59], v[28:31]
	ds_read_b128 v[60:63], v200 offset:128
	s_waitcnt lgkmcnt(0)
	v_mfma_f32_16x16x32_bf16 v[0:3], v[60:63], v[56:59], v[0:3]
	ds_read_b128 v[56:59], v48 offset:192
	ds_read_b128 v[60:63], v196 offset:192
	s_waitcnt lgkmcnt(0)
	v_mfma_f32_16x16x32_bf16 v[4:7], v[60:63], v[56:59], v[4:7]
	ds_read_b128 v[60:63], v196 offset:8640
	s_waitcnt lgkmcnt(0)
	v_mfma_f32_16x16x32_bf16 v[8:11], v[60:63], v[56:59], v[8:11]
	ds_read_b128 v[60:63], v196 offset:17088
	s_waitcnt lgkmcnt(0)
	v_mfma_f32_16x16x32_bf16 v[12:15], v[60:63], v[56:59], v[12:15]
	ds_read_b128 v[60:63], v196 offset:25536
	s_waitcnt lgkmcnt(0)
	v_mfma_f32_16x16x32_bf16 v[16:19], v[60:63], v[56:59], v[16:19]
	ds_read_b128 v[60:63], v196 offset:33984
	s_waitcnt lgkmcnt(0)
	v_mfma_f32_16x16x32_bf16 v[20:23], v[60:63], v[56:59], v[20:23]
	ds_read_b128 v[60:63], v196 offset:42432
	s_waitcnt lgkmcnt(0)
	v_mfma_f32_16x16x32_bf16 v[24:27], v[60:63], v[56:59], v[24:27]
	ds_read_b128 v[60:63], v196 offset:50880
	s_waitcnt lgkmcnt(0)
	v_mfma_f32_16x16x32_bf16 v[28:31], v[60:63], v[56:59], v[28:31]
	ds_read_b128 v[60:63], v200 offset:192
	s_waitcnt lgkmcnt(0)
	v_mfma_f32_16x16x32_bf16 v[0:3], v[60:63], v[56:59], v[0:3]
	ds_read_b128 v[56:59], v48 offset:256
	ds_read_b128 v[60:63], v196 offset:256
	s_waitcnt lgkmcnt(0)
	v_mfma_f32_16x16x32_bf16 v[4:7], v[60:63], v[56:59], v[4:7]
	ds_read_b128 v[60:63], v196 offset:8704
	s_waitcnt lgkmcnt(0)
	v_mfma_f32_16x16x32_bf16 v[8:11], v[60:63], v[56:59], v[8:11]
	ds_read_b128 v[60:63], v196 offset:17152
	s_waitcnt lgkmcnt(0)
	v_mfma_f32_16x16x32_bf16 v[12:15], v[60:63], v[56:59], v[12:15]
	ds_read_b128 v[60:63], v196 offset:25600
	s_waitcnt lgkmcnt(0)
	v_mfma_f32_16x16x32_bf16 v[16:19], v[60:63], v[56:59], v[16:19]
	ds_read_b128 v[60:63], v196 offset:34048
	s_waitcnt lgkmcnt(0)
	v_mfma_f32_16x16x32_bf16 v[20:23], v[60:63], v[56:59], v[20:23]
	ds_read_b128 v[60:63], v196 offset:42496
	s_waitcnt lgkmcnt(0)
	v_mfma_f32_16x16x32_bf16 v[24:27], v[60:63], v[56:59], v[24:27]
	ds_read_b128 v[60:63], v196 offset:50944
	s_waitcnt lgkmcnt(0)
	v_mfma_f32_16x16x32_bf16 v[28:31], v[60:63], v[56:59], v[28:31]
	ds_read_b128 v[60:63], v200 offset:256
	s_waitcnt lgkmcnt(0)
	v_mfma_f32_16x16x32_bf16 v[0:3], v[60:63], v[56:59], v[0:3]
	ds_read_b128 v[56:59], v48 offset:320
	ds_read_b128 v[60:63], v196 offset:320
	s_waitcnt lgkmcnt(0)
	v_mfma_f32_16x16x32_bf16 v[4:7], v[60:63], v[56:59], v[4:7]
	ds_read_b128 v[60:63], v196 offset:8768
	s_waitcnt lgkmcnt(0)
	v_mfma_f32_16x16x32_bf16 v[8:11], v[60:63], v[56:59], v[8:11]
	ds_read_b128 v[60:63], v196 offset:17216
	s_waitcnt lgkmcnt(0)
	v_mfma_f32_16x16x32_bf16 v[12:15], v[60:63], v[56:59], v[12:15]
	ds_read_b128 v[60:63], v196 offset:25664
	s_waitcnt lgkmcnt(0)
	v_mfma_f32_16x16x32_bf16 v[16:19], v[60:63], v[56:59], v[16:19]
	ds_read_b128 v[60:63], v196 offset:34112
	s_waitcnt lgkmcnt(0)
	v_mfma_f32_16x16x32_bf16 v[20:23], v[60:63], v[56:59], v[20:23]
	ds_read_b128 v[60:63], v196 offset:42560
	s_waitcnt lgkmcnt(0)
	v_mfma_f32_16x16x32_bf16 v[24:27], v[60:63], v[56:59], v[24:27]
	ds_read_b128 v[60:63], v196 offset:51008
	s_waitcnt lgkmcnt(0)
	v_mfma_f32_16x16x32_bf16 v[28:31], v[60:63], v[56:59], v[28:31]
	ds_read_b128 v[60:63], v200 offset:320
	s_waitcnt lgkmcnt(0)
	v_mfma_f32_16x16x32_bf16 v[0:3], v[60:63], v[56:59], v[0:3]
	ds_read_b128 v[56:59], v48 offset:384
	ds_read_b128 v[60:63], v196 offset:384
	s_waitcnt lgkmcnt(0)
	v_mfma_f32_16x16x32_bf16 v[4:7], v[60:63], v[56:59], v[4:7]
	ds_read_b128 v[60:63], v196 offset:8832
	s_waitcnt lgkmcnt(0)
	v_mfma_f32_16x16x32_bf16 v[8:11], v[60:63], v[56:59], v[8:11]
	ds_read_b128 v[60:63], v196 offset:17280
	s_waitcnt lgkmcnt(0)
	v_mfma_f32_16x16x32_bf16 v[12:15], v[60:63], v[56:59], v[12:15]
	ds_read_b128 v[60:63], v196 offset:25728
	s_waitcnt lgkmcnt(0)
	v_mfma_f32_16x16x32_bf16 v[60:63], v[60:63], v[56:59], v[16:19]
	s_nop 2
	ds_read_b128 v[16:19], v196 offset:34176
	s_waitcnt lgkmcnt(0)
	v_mfma_f32_16x16x32_bf16 v[114:117], v[16:19], v[56:59], v[20:23]
	ds_read_b128 v[16:19], v196 offset:42624
	s_waitcnt lgkmcnt(0)
	v_mfma_f32_16x16x32_bf16 v[24:27], v[16:19], v[56:59], v[24:27]
	ds_read_b128 v[16:19], v196 offset:51072
	s_waitcnt lgkmcnt(0)
	v_mfma_f32_16x16x32_bf16 v[118:121], v[16:19], v[56:59], v[28:31]
	ds_read_b128 v[16:19], v200 offset:384
	s_waitcnt lgkmcnt(0)
	v_mfma_f32_16x16x32_bf16 v[0:3], v[16:19], v[56:59], v[0:3]
	ds_read_b128 v[56:59], v48 offset:448
	ds_read_b128 v[16:19], v196 offset:448
	s_waitcnt lgkmcnt(0)
	v_mfma_f32_16x16x32_bf16 v[4:7], v[16:19], v[56:59], v[4:7]
	ds_read_b128 v[16:19], v196 offset:8896
	s_waitcnt lgkmcnt(0)
	v_mfma_f32_16x16x32_bf16 v[16:19], v[16:19], v[56:59], v[8:11]
	s_nop 2
	ds_read_b128 v[8:11], v196 offset:17344
	s_waitcnt lgkmcnt(0)
	v_mfma_f32_16x16x32_bf16 v[20:23], v[8:11], v[56:59], v[12:15]
	ds_read_b128 v[8:11], v196 offset:25792
	s_nop 1
	ds_read_b128 v[12:15], v196 offset:42688
	s_waitcnt lgkmcnt(1)
	v_mfma_f32_16x16x32_bf16 v[28:31], v[8:11], v[56:59], v[60:63]
	ds_read_b128 v[8:11], v196 offset:34240
	s_nop 1
	ds_read_b128 v[60:63], v200 offset:448
	s_waitcnt lgkmcnt(2)
	v_mfma_f32_16x16x32_bf16 v[12:15], v[12:15], v[56:59], v[24:27]
	s_nop 2
	ds_read_b128 v[24:27], v196 offset:51136
	s_waitcnt lgkmcnt(2)
	v_mfma_f32_16x16x32_bf16 v[8:11], v[8:11], v[56:59], v[114:117]
	s_waitcnt lgkmcnt(0)
	s_barrier
	v_mfma_f32_16x16x32_bf16 v[24:27], v[24:27], v[56:59], v[118:121]
	v_mfma_f32_16x16x32_bf16 v[0:3], v[60:63], v[56:59], v[0:3]
	s_waitcnt vmcnt(6)
	v_and_b32_e32 v250, 0xffff, v206
	v_lshrrev_b32_e32 v251, 16, v206
	v_lshl_or_b32 v250, v210, 16, v250
	v_and_or_b32 v251, v210, s54, v251
	ds_write2_b32 v198, v250, v251 offset1:132
	v_and_b32_e32 v250, 0xffff, v207
	v_lshrrev_b32_e32 v251, 16, v207
	v_lshl_or_b32 v250, v211, 16, v250
	v_and_or_b32 v251, v211, s54, v251
	ds_write2_b32 v49, v250, v251 offset0:8 offset1:140
	v_and_b32_e32 v250, 0xffff, v208
	v_lshrrev_b32_e32 v251, 16, v208
	v_lshl_or_b32 v250, v212, 16, v250
	v_and_or_b32 v251, v212, s54, v251
	ds_write2_b32 v50, v250, v251 offset0:16 offset1:148
	v_and_b32_e32 v250, 0xffff, v209
	v_lshrrev_b32_e32 v251, 16, v209
	v_lshl_or_b32 v250, v213, 16, v250
	v_and_or_b32 v251, v213, s54, v251
	ds_write2_b32 v51, v250, v251 offset0:24 offset1:156
	s_waitcnt vmcnt(4)
	v_and_b32_e32 v250, 0xffff, v214
	v_lshrrev_b32_e32 v251, 16, v214
	v_lshl_or_b32 v250, v218, 16, v250
	v_and_or_b32 v251, v218, s54, v251
	ds_write2_b32 v199, v250, v251 offset1:132
	v_and_b32_e32 v250, 0xffff, v215
	v_lshrrev_b32_e32 v251, 16, v215
	v_lshl_or_b32 v250, v219, 16, v250
	v_and_or_b32 v251, v219, s54, v251
	ds_write2_b32 v52, v250, v251 offset0:8 offset1:140
	v_and_b32_e32 v250, 0xffff, v216
	v_lshrrev_b32_e32 v251, 16, v216
	v_lshl_or_b32 v250, v220, 16, v250
	v_and_or_b32 v251, v220, s54, v251
	ds_write2_b32 v53, v250, v251 offset0:16 offset1:148
	v_and_b32_e32 v250, 0xffff, v217
	v_lshrrev_b32_e32 v251, 16, v217
	v_lshl_or_b32 v250, v221, 16, v250
	v_and_or_b32 v251, v221, s54, v251
	ds_write2_b32 v54, v250, v251 offset0:24 offset1:156
	s_waitcnt vmcnt(3)
	ds_write_b128 v86, v[222:225] offset:256
	s_waitcnt vmcnt(2)
	ds_write_b128 v88, v[230:233] offset:256
	s_waitcnt vmcnt(1)
	ds_write_b128 v90, v[234:237] offset:256
	s_waitcnt vmcnt(0)
	ds_write_b128 v92, v[238:241] offset:256
	s_waitcnt lgkmcnt(0)
	s_barrier
	ds_read_b128 v[32:35], v48
	ds_read_b128 v[36:39], v196
	ds_read_b128 v[40:43], v196 offset:8448
	ds_read_b128 v[114:117], v196 offset:50688
	ds_read_b128 v[44:47], v196 offset:16896
	ds_read_b128 v[50:53], v196 offset:25344
	ds_read_b128 v[54:57], v196 offset:33792
	ds_read_b128 v[58:61], v196 offset:42240
	ds_read_b128 v[118:121], v200
	s_waitcnt lgkmcnt(7)
	v_mfma_f32_16x16x32_bf16 v[36:39], v[36:39], v[32:35], 0
	s_waitcnt lgkmcnt(6)
	v_mfma_f32_16x16x32_bf16 v[40:43], v[40:43], v[32:35], 0
	s_waitcnt lgkmcnt(4)
	v_mfma_f32_16x16x32_bf16 v[44:47], v[44:47], v[32:35], 0
	s_waitcnt lgkmcnt(3)
	v_mfma_f32_16x16x32_bf16 v[50:53], v[50:53], v[32:35], 0
	s_waitcnt lgkmcnt(2)
	v_mfma_f32_16x16x32_bf16 v[54:57], v[54:57], v[32:35], 0
	s_waitcnt lgkmcnt(1)
	v_mfma_f32_16x16x32_bf16 v[58:61], v[58:61], v[32:35], 0
	v_mfma_f32_16x16x32_bf16 v[114:117], v[114:117], v[32:35], 0
	s_waitcnt lgkmcnt(0)
	v_mfma_f32_16x16x32_bf16 v[32:35], v[118:121], v[32:35], 0
	ds_read_b128 v[118:121], v48 offset:64
	ds_read_b128 v[122:125], v196 offset:64
	s_waitcnt lgkmcnt(0)
	v_mfma_f32_16x16x32_bf16 v[36:39], v[122:125], v[118:121], v[36:39]
	ds_read_b128 v[122:125], v196 offset:8512
	s_waitcnt lgkmcnt(0)
	v_mfma_f32_16x16x32_bf16 v[40:43], v[122:125], v[118:121], v[40:43]
	ds_read_b128 v[122:125], v196 offset:16960
	s_waitcnt lgkmcnt(0)
	v_mfma_f32_16x16x32_bf16 v[44:47], v[122:125], v[118:121], v[44:47]
	ds_read_b128 v[122:125], v196 offset:25408
	s_waitcnt lgkmcnt(0)
	v_mfma_f32_16x16x32_bf16 v[50:53], v[122:125], v[118:121], v[50:53]
	ds_read_b128 v[122:125], v196 offset:33856
	s_waitcnt lgkmcnt(0)
	v_mfma_f32_16x16x32_bf16 v[54:57], v[122:125], v[118:121], v[54:57]
	ds_read_b128 v[122:125], v196 offset:42304
	s_waitcnt lgkmcnt(0)
	v_mfma_f32_16x16x32_bf16 v[58:61], v[122:125], v[118:121], v[58:61]
	ds_read_b128 v[122:125], v196 offset:50752
	s_waitcnt lgkmcnt(0)
	v_mfma_f32_16x16x32_bf16 v[114:117], v[122:125], v[118:121], v[114:117]
	ds_read_b128 v[122:125], v200 offset:64
	s_waitcnt lgkmcnt(0)
	v_mfma_f32_16x16x32_bf16 v[32:35], v[122:125], v[118:121], v[32:35]
	ds_read_b128 v[118:121], v48 offset:128
	ds_read_b128 v[122:125], v196 offset:128
	s_waitcnt lgkmcnt(0)
	v_mfma_f32_16x16x32_bf16 v[36:39], v[122:125], v[118:121], v[36:39]
	ds_read_b128 v[122:125], v196 offset:8576
	s_waitcnt lgkmcnt(0)
	v_mfma_f32_16x16x32_bf16 v[40:43], v[122:125], v[118:121], v[40:43]
	ds_read_b128 v[122:125], v196 offset:17024
	s_waitcnt lgkmcnt(0)
	v_mfma_f32_16x16x32_bf16 v[44:47], v[122:125], v[118:121], v[44:47]
	ds_read_b128 v[122:125], v196 offset:25472
	s_waitcnt lgkmcnt(0)
	v_mfma_f32_16x16x32_bf16 v[50:53], v[122:125], v[118:121], v[50:53]
	ds_read_b128 v[122:125], v196 offset:33920
	s_waitcnt lgkmcnt(0)
	v_mfma_f32_16x16x32_bf16 v[54:57], v[122:125], v[118:121], v[54:57]
	ds_read_b128 v[122:125], v196 offset:42368
	s_waitcnt lgkmcnt(0)
	v_mfma_f32_16x16x32_bf16 v[58:61], v[122:125], v[118:121], v[58:61]
	ds_read_b128 v[122:125], v196 offset:50816
	s_waitcnt lgkmcnt(0)
	v_mfma_f32_16x16x32_bf16 v[114:117], v[122:125], v[118:121], v[114:117]
	ds_read_b128 v[122:125], v200 offset:128
	s_waitcnt lgkmcnt(0)
	v_mfma_f32_16x16x32_bf16 v[32:35], v[122:125], v[118:121], v[32:35]
	ds_read_b128 v[118:121], v48 offset:192
	ds_read_b128 v[122:125], v196 offset:192
	s_waitcnt lgkmcnt(0)
	v_mfma_f32_16x16x32_bf16 v[36:39], v[122:125], v[118:121], v[36:39]
	ds_read_b128 v[122:125], v196 offset:8640
	s_waitcnt lgkmcnt(0)
	v_mfma_f32_16x16x32_bf16 v[40:43], v[122:125], v[118:121], v[40:43]
	ds_read_b128 v[122:125], v196 offset:17088
	s_waitcnt lgkmcnt(0)
	v_mfma_f32_16x16x32_bf16 v[44:47], v[122:125], v[118:121], v[44:47]
	ds_read_b128 v[122:125], v196 offset:25536
	s_waitcnt lgkmcnt(0)
	v_mfma_f32_16x16x32_bf16 v[50:53], v[122:125], v[118:121], v[50:53]
	ds_read_b128 v[122:125], v196 offset:33984
	s_waitcnt lgkmcnt(0)
	v_mfma_f32_16x16x32_bf16 v[54:57], v[122:125], v[118:121], v[54:57]
	ds_read_b128 v[122:125], v196 offset:42432
	s_waitcnt lgkmcnt(0)
	v_mfma_f32_16x16x32_bf16 v[58:61], v[122:125], v[118:121], v[58:61]
	ds_read_b128 v[122:125], v196 offset:50880
	s_waitcnt lgkmcnt(0)
	v_mfma_f32_16x16x32_bf16 v[114:117], v[122:125], v[118:121], v[114:117]
	ds_read_b128 v[122:125], v200 offset:192
	s_waitcnt lgkmcnt(0)
	v_mfma_f32_16x16x32_bf16 v[32:35], v[122:125], v[118:121], v[32:35]
	ds_read_b128 v[118:121], v48 offset:256
	ds_read_b128 v[122:125], v196 offset:256
	s_waitcnt lgkmcnt(0)
	v_mfma_f32_16x16x32_bf16 v[36:39], v[122:125], v[118:121], v[36:39]
	ds_read_b128 v[122:125], v196 offset:8704
	s_waitcnt lgkmcnt(0)
	v_mfma_f32_16x16x32_bf16 v[40:43], v[122:125], v[118:121], v[40:43]
	ds_read_b128 v[122:125], v196 offset:17152
	s_waitcnt lgkmcnt(0)
	v_mfma_f32_16x16x32_bf16 v[44:47], v[122:125], v[118:121], v[44:47]
	ds_read_b128 v[122:125], v196 offset:25600
	s_waitcnt lgkmcnt(0)
	v_mfma_f32_16x16x32_bf16 v[50:53], v[122:125], v[118:121], v[50:53]
	ds_read_b128 v[122:125], v196 offset:34048
	s_waitcnt lgkmcnt(0)
	v_mfma_f32_16x16x32_bf16 v[54:57], v[122:125], v[118:121], v[54:57]
	ds_read_b128 v[122:125], v196 offset:42496
	s_waitcnt lgkmcnt(0)
	v_mfma_f32_16x16x32_bf16 v[58:61], v[122:125], v[118:121], v[58:61]
	ds_read_b128 v[122:125], v196 offset:50944
	s_waitcnt lgkmcnt(0)
	v_mfma_f32_16x16x32_bf16 v[114:117], v[122:125], v[118:121], v[114:117]
	ds_read_b128 v[122:125], v200 offset:256
	s_waitcnt lgkmcnt(0)
	v_mfma_f32_16x16x32_bf16 v[32:35], v[122:125], v[118:121], v[32:35]
	ds_read_b128 v[118:121], v48 offset:320
	ds_read_b128 v[122:125], v196 offset:320
	s_waitcnt lgkmcnt(0)
	v_mfma_f32_16x16x32_bf16 v[36:39], v[122:125], v[118:121], v[36:39]
	ds_read_b128 v[122:125], v196 offset:8768
	s_waitcnt lgkmcnt(0)
	v_mfma_f32_16x16x32_bf16 v[40:43], v[122:125], v[118:121], v[40:43]
	ds_read_b128 v[122:125], v196 offset:17216
	s_waitcnt lgkmcnt(0)
	v_mfma_f32_16x16x32_bf16 v[44:47], v[122:125], v[118:121], v[44:47]
	ds_read_b128 v[122:125], v196 offset:25664
	s_waitcnt lgkmcnt(0)
	v_mfma_f32_16x16x32_bf16 v[50:53], v[122:125], v[118:121], v[50:53]
	ds_read_b128 v[122:125], v196 offset:34112
	s_waitcnt lgkmcnt(0)
	v_mfma_f32_16x16x32_bf16 v[54:57], v[122:125], v[118:121], v[54:57]
	ds_read_b128 v[122:125], v196 offset:42560
	s_waitcnt lgkmcnt(0)
	v_mfma_f32_16x16x32_bf16 v[58:61], v[122:125], v[118:121], v[58:61]
	ds_read_b128 v[122:125], v196 offset:51008
	s_waitcnt lgkmcnt(0)
	v_mfma_f32_16x16x32_bf16 v[114:117], v[122:125], v[118:121], v[114:117]
	ds_read_b128 v[122:125], v200 offset:320
	s_waitcnt lgkmcnt(0)
	v_mfma_f32_16x16x32_bf16 v[32:35], v[122:125], v[118:121], v[32:35]
	ds_read_b128 v[118:121], v48 offset:384
	ds_read_b128 v[122:125], v196 offset:384
	s_waitcnt lgkmcnt(0)
	v_mfma_f32_16x16x32_bf16 v[36:39], v[122:125], v[118:121], v[36:39]
	ds_read_b128 v[122:125], v196 offset:8832
	s_waitcnt lgkmcnt(0)
	v_mfma_f32_16x16x32_bf16 v[40:43], v[122:125], v[118:121], v[40:43]
	ds_read_b128 v[122:125], v196 offset:17280
	s_waitcnt lgkmcnt(0)
	v_mfma_f32_16x16x32_bf16 v[44:47], v[122:125], v[118:121], v[44:47]
	ds_read_b128 v[122:125], v196 offset:25728
	s_waitcnt lgkmcnt(0)
	v_mfma_f32_16x16x32_bf16 v[50:53], v[122:125], v[118:121], v[50:53]
	ds_read_b128 v[122:125], v196 offset:34176
	s_waitcnt lgkmcnt(0)
	v_mfma_f32_16x16x32_bf16 v[54:57], v[122:125], v[118:121], v[54:57]
	ds_read_b128 v[122:125], v196 offset:42624
	s_waitcnt lgkmcnt(0)
	v_mfma_f32_16x16x32_bf16 v[58:61], v[122:125], v[118:121], v[58:61]
	ds_read_b128 v[122:125], v196 offset:51072
	s_waitcnt lgkmcnt(0)
	v_mfma_f32_16x16x32_bf16 v[114:117], v[122:125], v[118:121], v[114:117]
	ds_read_b128 v[122:125], v200 offset:384
	s_waitcnt lgkmcnt(0)
	v_mfma_f32_16x16x32_bf16 v[118:121], v[122:125], v[118:121], v[32:35]
	ds_read_b128 v[122:125], v48 offset:448
	s_nop 1
	ds_read_b128 v[32:35], v196 offset:448
	s_waitcnt lgkmcnt(0)
	v_mfma_f32_16x16x32_bf16 v[32:35], v[32:35], v[122:125], v[36:39]
	s_nop 2
	ds_read_b128 v[36:39], v196 offset:8896
	s_waitcnt lgkmcnt(0)
	v_mfma_f32_16x16x32_bf16 v[40:43], v[36:39], v[122:125], v[40:43]
	ds_read_b128 v[36:39], v196 offset:17344
	s_waitcnt lgkmcnt(0)
	v_mfma_f32_16x16x32_bf16 v[36:39], v[36:39], v[122:125], v[44:47]
	s_nop 2
	ds_read_b128 v[44:47], v196 offset:25792
	s_waitcnt lgkmcnt(0)
	v_mfma_f32_16x16x32_bf16 v[44:47], v[44:47], v[122:125], v[50:53]
	s_nop 2
	ds_read_b128 v[48:51], v196 offset:34240
	s_waitcnt lgkmcnt(0)
	v_mfma_f32_16x16x32_bf16 v[52:55], v[48:51], v[122:125], v[54:57]
	ds_read_b128 v[48:51], v196 offset:42688
	s_waitcnt lgkmcnt(0)
	v_mfma_f32_16x16x32_bf16 v[48:51], v[48:51], v[122:125], v[58:61]
	s_nop 2
	ds_read_b128 v[56:59], v196 offset:51136
	ds_read_b128 v[60:63], v200 offset:448
	s_waitcnt lgkmcnt(1)
	v_mfma_f32_16x16x32_bf16 v[56:59], v[56:59], v[122:125], v[114:117]
	s_nop 2
	v_rcp_f32_e32 v114, v109
	s_nop 0
	v_fma_f32 v115, -v109, v114, 1.0
	v_fmac_f32_e32 v114, v115, v114
	v_div_scale_f32 v115, vcc, 1.0, v107, 1.0
	v_mul_f32_e32 v116, v115, v114
	v_fma_f32 v117, -v109, v116, v115
	v_fmac_f32_e32 v116, v117, v114
	v_fma_f32 v109, -v109, v116, v115
	v_div_fmas_f32 v109, v109, v114, v116
	v_div_fixup_f32 v204, v109, v107, 1.0
	v_pk_mul_f32 v[146:147], v[204:205], v[6:7] op_sel_hi:[0,1]
	v_pk_mul_f32 v[148:149], v[204:205], v[4:5] op_sel_hi:[0,1]
	v_pk_mul_f32 v[4:5], v[148:149], v[148:149]
	v_pk_mul_f32 v[6:7], v[146:147], v[146:147]
	v_pk_mul_f32 v[142:143], v[204:205], v[18:19] op_sel_hi:[0,1]
	v_pk_mul_f32 v[144:145], v[204:205], v[16:17] op_sel_hi:[0,1]
	v_pk_mov_b32 v[114:115], v[4:5], v[6:7] op_sel:[1,0]
	v_mov_b32_e32 v5, v7
	v_pk_mul_f32 v[6:7], v[144:145], v[144:145]
	v_pk_mul_f32 v[16:17], v[142:143], v[142:143]
	v_pk_add_f32 v[4:5], v[114:115], v[4:5]
	v_pk_mov_b32 v[18:19], v[6:7], v[16:17] op_sel:[1,0]
	v_mov_b32_e32 v7, v17
	v_pk_add_f32 v[6:7], v[18:19], v[6:7]
	v_pk_mul_f32 v[136:137], v[204:205], v[28:29] op_sel_hi:[0,1]
	v_mul_f32_e32 v16, v136, v136
	v_mul_f32_e32 v17, v137, v137
	v_pk_add_f32 v[4:5], v[4:5], v[4:5] op_sel:[0,1] op_sel_hi:[1,0]
	v_pk_add_f32 v[6:7], v[6:7], v[6:7] op_sel:[0,1] op_sel_hi:[1,0]
	v_pk_mul_f32 v[138:139], v[204:205], v[22:23] op_sel_hi:[0,1]
	v_pk_mul_f32 v[140:141], v[204:205], v[20:21] op_sel_hi:[0,1]
	v_mov_b32_e32 v5, v16
	v_mov_b32_e32 v7, v17
	v_pk_mul_f32 v[134:135], v[204:205], v[30:31] op_sel_hi:[0,1]
	v_pk_add_f32 v[4:5], v[4:5], v[6:7]
	v_mul_f32_e32 v6, v141, v141
	v_mul_f32_e32 v16, v139, v139
	v_mul_f32_e32 v18, v134, v134
	v_mul_f32_e32 v19, v135, v135
	v_pk_fma_f32 v[6:7], v[140:141], v[140:141], v[6:7] op_sel_hi:[1,1,0]
	v_pk_fma_f32 v[16:17], v[138:139], v[138:139], v[16:17] op_sel_hi:[1,1,0]
	v_mov_b32_e32 v7, v18
	v_mov_b32_e32 v17, v19
	v_pk_add_f32 v[6:7], v[6:7], v[16:17]
	v_pk_mul_f32 v[130:131], v[204:205], v[10:11] op_sel_hi:[0,1]
	v_pk_mul_f32 v[132:133], v[204:205], v[8:9] op_sel_hi:[0,1]
	v_pk_add_f32 v[4:5], v[4:5], v[6:7]
	v_pk_mul_f32 v[6:7], v[132:133], v[132:133]
	v_pk_mul_f32 v[8:9], v[130:131], v[130:131]
	s_waitcnt lgkmcnt(0)
	v_mfma_f32_16x16x32_bf16 v[60:63], v[60:63], v[122:125], v[118:121]
	v_pk_mov_b32 v[10:11], v[6:7], v[8:9] op_sel:[1,0]
	v_mov_b32_e32 v7, v9
	v_pk_add_f32 v[6:7], v[10:11], v[6:7]
	v_pk_mul_f32 v[124:125], v[204:205], v[24:25] op_sel_hi:[0,1]
	v_mul_f32_e32 v8, v124, v124
	v_mul_f32_e32 v9, v125, v125
	v_pk_add_f32 v[4:5], v[4:5], v[4:5] op_sel:[0,1] op_sel_hi:[1,0]
	v_pk_add_f32 v[6:7], v[6:7], v[6:7] op_sel:[0,1] op_sel_hi:[1,0]
	v_pk_mul_f32 v[126:127], v[204:205], v[14:15] op_sel_hi:[0,1]
	v_pk_mul_f32 v[128:129], v[204:205], v[12:13] op_sel_hi:[0,1]
	v_mov_b32_e32 v5, v8
	v_mov_b32_e32 v7, v9
	v_pk_mul_f32 v[122:123], v[204:205], v[26:27] op_sel_hi:[0,1]
	v_pk_add_f32 v[4:5], v[4:5], v[6:7]
	v_mul_f32_e32 v6, v129, v129
	v_mul_f32_e32 v8, v127, v127
	v_mul_f32_e32 v10, v122, v122
	v_mul_f32_e32 v11, v123, v123
	v_pk_fma_f32 v[6:7], v[128:129], v[128:129], v[6:7] op_sel_hi:[1,1,0]
	v_pk_fma_f32 v[8:9], v[126:127], v[126:127], v[8:9] op_sel_hi:[1,1,0]
	v_mov_b32_e32 v7, v10
	v_mov_b32_e32 v9, v11
	v_pk_mul_f32 v[118:119], v[204:205], v[2:3] op_sel_hi:[0,1]
	v_pk_mul_f32 v[120:121], v[204:205], v[0:1] op_sel_hi:[0,1]
	v_pk_add_f32 v[6:7], v[6:7], v[8:9]
	v_pk_mul_f32 v[0:1], v[120:121], v[120:121]
	v_pk_mul_f32 v[2:3], v[118:119], v[118:119]
	v_pk_add_f32 v[4:5], v[4:5], v[6:7]
	v_pk_mov_b32 v[6:7], v[0:1], v[2:3] op_sel:[1,0]
	v_mov_b32_e32 v1, v3
	v_pk_add_f32 v[0:1], v[6:7], v[0:1]
	v_pk_mul_f32 v[40:41], v[204:205], v[40:41] op_sel_hi:[0,1]
	v_mul_f32_e32 v6, v40, v40
	v_mul_f32_e32 v7, v41, v41
	v_pk_add_f32 v[2:3], v[4:5], v[4:5] op_sel:[0,1] op_sel_hi:[1,0]
	v_pk_add_f32 v[0:1], v[0:1], v[0:1] op_sel:[0,1] op_sel_hi:[1,0]
	v_pk_mul_f32 v[114:115], v[204:205], v[34:35] op_sel_hi:[0,1]
	v_pk_mul_f32 v[116:117], v[204:205], v[32:33] op_sel_hi:[0,1]
	v_mov_b32_e32 v3, v6
	v_mov_b32_e32 v1, v7
	v_pk_mul_f32 v[34:35], v[204:205], v[42:43] op_sel_hi:[0,1]
	v_pk_add_f32 v[0:1], v[2:3], v[0:1]
	v_mul_f32_e32 v2, v117, v117
	v_mul_f32_e32 v4, v115, v115
	v_mul_f32_e32 v8, v34, v34
	v_mul_f32_e32 v9, v35, v35
	v_pk_fma_f32 v[2:3], v[116:117], v[116:117], v[2:3] op_sel_hi:[1,1,0]
	v_pk_fma_f32 v[4:5], v[114:115], v[114:115], v[4:5] op_sel_hi:[1,1,0]
	v_mov_b32_e32 v3, v8
	v_mov_b32_e32 v5, v9
	v_pk_add_f32 v[2:3], v[2:3], v[4:5]
	v_pk_mul_f32 v[30:31], v[204:205], v[38:39] op_sel_hi:[0,1]
	v_pk_mul_f32 v[32:33], v[204:205], v[36:37] op_sel_hi:[0,1]
	v_pk_add_f32 v[0:1], v[0:1], v[2:3]
	v_pk_mul_f32 v[2:3], v[32:33], v[32:33]
	v_pk_mul_f32 v[4:5], v[30:31], v[30:31]
	v_pk_mul_f32 v[24:25], v[204:205], v[52:53] op_sel_hi:[0,1]
	v_pk_mov_b32 v[6:7], v[2:3], v[4:5] op_sel:[1,0]
	v_mov_b32_e32 v3, v5
	v_pk_add_f32 v[2:3], v[6:7], v[2:3]
	v_mul_f32_e32 v4, v24, v24
	v_mul_f32_e32 v5, v25, v25
	v_pk_add_f32 v[0:1], v[0:1], v[0:1] op_sel:[0,1] op_sel_hi:[1,0]
	v_pk_add_f32 v[2:3], v[2:3], v[2:3] op_sel:[0,1] op_sel_hi:[1,0]
	v_pk_mul_f32 v[26:27], v[204:205], v[46:47] op_sel_hi:[0,1]
	v_pk_mul_f32 v[28:29], v[204:205], v[44:45] op_sel_hi:[0,1]
	v_mov_b32_e32 v1, v4
	v_mov_b32_e32 v3, v5
	v_pk_mul_f32 v[22:23], v[204:205], v[54:55] op_sel_hi:[0,1]
	v_pk_add_f32 v[0:1], v[0:1], v[2:3]
	v_mul_f32_e32 v2, v29, v29
	v_mul_f32_e32 v4, v27, v27
	v_mul_f32_e32 v6, v22, v22
	v_mul_f32_e32 v7, v23, v23
	v_pk_fma_f32 v[2:3], v[28:29], v[28:29], v[2:3] op_sel_hi:[1,1,0]
	v_pk_fma_f32 v[4:5], v[26:27], v[26:27], v[4:5] op_sel_hi:[1,1,0]
	v_mov_b32_e32 v3, v6
	v_mov_b32_e32 v5, v7
	v_pk_add_f32 v[2:3], v[2:3], v[4:5]
	v_pk_mul_f32 v[18:19], v[204:205], v[50:51] op_sel_hi:[0,1]
	v_pk_mul_f32 v[20:21], v[204:205], v[48:49] op_sel_hi:[0,1]
	v_pk_add_f32 v[0:1], v[0:1], v[2:3]
	v_pk_mul_f32 v[2:3], v[20:21], v[20:21]
	v_pk_mul_f32 v[4:5], v[18:19], v[18:19]
	v_pk_add_f32 v[0:1], v[0:1], v[0:1] op_sel:[0,1] op_sel_hi:[1,0]
	v_pk_mov_b32 v[6:7], v[2:3], v[4:5] op_sel:[1,0]
	v_mov_b32_e32 v3, v5
	v_pk_add_f32 v[2:3], v[6:7], v[2:3]
	v_pk_mul_f32 v[6:7], v[204:205], v[60:61] op_sel_hi:[0,1]
	v_mul_f32_e32 v8, v6, v6
	v_mul_f32_e32 v9, v7, v7
	v_pk_add_f32 v[2:3], v[2:3], v[2:3] op_sel:[0,1] op_sel_hi:[1,0]
	v_pk_mul_f32 v[10:11], v[204:205], v[58:59] op_sel_hi:[0,1]
	v_pk_mul_f32 v[12:13], v[204:205], v[56:57] op_sel_hi:[0,1]
	v_mov_b32_e32 v1, v8
	v_mov_b32_e32 v3, v9
	v_pk_mul_f32 v[4:5], v[204:205], v[62:63] op_sel_hi:[0,1]
	v_pk_add_f32 v[0:1], v[0:1], v[2:3]
	v_mul_f32_e32 v2, v13, v13
	v_mul_f32_e32 v8, v11, v11
	v_mul_f32_e32 v14, v4, v4
	v_mul_f32_e32 v15, v5, v5
	v_pk_fma_f32 v[2:3], v[12:13], v[12:13], v[2:3] op_sel_hi:[1,1,0]
	v_pk_fma_f32 v[8:9], v[10:11], v[10:11], v[8:9] op_sel_hi:[1,1,0]
	v_mov_b32_e32 v3, v14
	v_mov_b32_e32 v9, v15
	v_pk_add_f32 v[2:3], v[2:3], v[8:9]
	v_lshl_add_u64 v[16:17], v[112:113], 0, s[20:21]
	v_pk_add_f32 v[0:1], v[0:1], v[2:3]
	v_mov_b32_e32 v109, v67
	v_add_f32_e32 v0, v0, v1
	ds_bpermute_b32 v1, v160, v0
	v_lshl_add_u64 v[38:39], v[16:17], 0, v[108:109]
	s_waitcnt lgkmcnt(0)
	v_add_f32_e32 v0, v0, v1
	ds_bpermute_b32 v1, v154, v0
	s_waitcnt lgkmcnt(0)
	v_add_f32_e32 v0, v0, v1
	v_fmamk_f32 v0, v0, 0x3b800000, v201
	v_cmp_gt_f32_e32 vcc, s48, v0
	v_mul_f32_e32 v1, 0x4b800000, v0
	s_mov_b64 s[48:49], 0x1000
	v_cndmask_b32_e32 v0, v0, v1, vcc
	v_rsq_f32_e32 v0, v0
	v_lshl_add_u64 v[16:17], v[38:39], 0, s[48:49]
	v_mul_f32_e32 v1, 0x45800000, v0
	v_cndmask_b32_e32 v8, v0, v1, vcc
	v_lshlrev_b64 v[0:1], 11, v[110:111]
	v_lshl_add_u64 v[0:1], s[92:93], 0, v[0:1]
	v_lshl_add_u64 v[36:37], v[0:1], 0, s[20:21]
	s_lshl_b32 s20, s58, 10
	v_lshl_add_u64 v[14:15], v[94:95], 0, s[20:21]
	s_movk_i32 s20, 0x1000
	v_add_co_u32_e32 v38, vcc, s20, v38
	global_load_dwordx4 v[0:3], v[14:15], off
	s_nop 0
	v_addc_co_u32_e32 v39, vcc, 0, v39, vcc
	global_load_dwordx2 v[38:39], v[38:39], off
	v_pk_mul_f32 v[42:43], v[148:149], v[8:9] op_sel_hi:[1,0]
	v_pk_mul_f32 v[44:45], v[146:147], v[8:9] op_sel_hi:[1,0]
	s_add_u32 s5, s5, s46
	s_addc_u32 s97, s97, s47
	s_add_i32 s33, s33, s52
	s_cmpk_lt_i32 s4, 0x400
	s_waitcnt vmcnt(1)
	v_pk_mul_f32 v[0:1], v[0:1], v[42:43]
	v_pk_mul_f32 v[2:3], v[2:3], v[44:45]
	s_waitcnt vmcnt(0)
	v_lshlrev_b32_e32 v9, 16, v38
	v_mul_f32_e32 v9, 0xbfb8aa3b, v9
	v_exp_f32_e32 v9, v9
	s_nop 0
	v_add_f32_e32 v9, 1.0, v9
	v_rcp_f32_e32 v42, v9
	v_and_b32_e32 v9, 0xffff0000, v38
	v_mul_f32_e32 v9, 0xbfb8aa3b, v9
	v_exp_f32_e32 v9, v9
	s_nop 0
	v_add_f32_e32 v9, 1.0, v9
	v_rcp_f32_e32 v43, v9
	v_pk_mul_f32 v[44:45], v[142:143], v[8:9] op_sel_hi:[1,0]
	v_pk_mul_f32 v[0:1], v[42:43], v[0:1]
	s_nop 0
	v_cvt_pk_bf16_f32 v38, v0, v1
	v_lshlrev_b32_e32 v0, 16, v39
	v_and_b32_e32 v1, 0xffff0000, v39
	v_mul_f32_e32 v0, 0xbfb8aa3b, v0
	v_mul_f32_e32 v1, 0xbfb8aa3b, v1
	v_exp_f32_e32 v0, v0
	v_exp_f32_e32 v1, v1
	v_pk_mul_f32 v[42:43], v[144:145], v[8:9] op_sel_hi:[1,0]
	v_add_f32_e32 v0, 1.0, v0
	v_add_f32_e32 v1, 1.0, v1
	v_rcp_f32_e32 v0, v0
	v_rcp_f32_e32 v1, v1
	s_nop 0
	v_pk_mul_f32 v[0:1], v[0:1], v[2:3]
	s_nop 0
	v_cvt_pk_bf16_f32 v39, v0, v1
	v_lshl_add_u64 v[0:1], v[36:37], 0, v[108:109]
	global_store_dwordx2 v[0:1], v[38:39], off
	global_load_dwordx4 v[36:39], v[14:15], off offset:64
	s_nop 0
	global_load_dwordx2 v[2:3], v[16:17], off offset:32
	s_waitcnt vmcnt(1)
	v_pk_mul_f32 v[36:37], v[36:37], v[42:43]
	s_waitcnt vmcnt(0)
	v_lshlrev_b32_e32 v9, 16, v2
	v_mul_f32_e32 v9, 0xbfb8aa3b, v9
	v_exp_f32_e32 v9, v9
	v_and_b32_e32 v2, 0xffff0000, v2
	v_mul_f32_e32 v2, 0xbfb8aa3b, v2
	v_exp_f32_e32 v2, v2
	v_add_f32_e32 v9, 1.0, v9
	v_rcp_f32_e32 v42, v9
	v_lshlrev_b32_e32 v9, 16, v3
	v_and_b32_e32 v3, 0xffff0000, v3
	v_add_f32_e32 v2, 1.0, v2
	v_mul_f32_e32 v9, 0xbfb8aa3b, v9
	v_mul_f32_e32 v3, 0xbfb8aa3b, v3
	v_rcp_f32_e32 v43, v2
	v_exp_f32_e32 v9, v9
	v_exp_f32_e32 v3, v3
	v_pk_mul_f32 v[38:39], v[38:39], v[44:45]
	v_pk_mul_f32 v[36:37], v[42:43], v[36:37]
	v_add_f32_e32 v9, 1.0, v9
	v_add_f32_e32 v3, 1.0, v3
	v_cvt_pk_bf16_f32 v2, v36, v37
	v_rcp_f32_e32 v36, v9
	v_rcp_f32_e32 v37, v3
	v_pk_mul_f32 v[42:43], v[140:141], v[8:9] op_sel_hi:[1,0]
	v_pk_mul_f32 v[44:45], v[138:139], v[8:9] op_sel_hi:[1,0]
	v_pk_mul_f32 v[36:37], v[36:37], v[38:39]
	s_nop 0
	v_cvt_pk_bf16_f32 v3, v36, v37
	global_store_dwordx2 v[0:1], v[2:3], off offset:32
	global_load_dwordx4 v[36:39], v[14:15], off offset:128
	s_nop 0
	global_load_dwordx2 v[2:3], v[16:17], off offset:64
	s_waitcnt vmcnt(1)
	v_pk_mul_f32 v[36:37], v[36:37], v[42:43]
	s_waitcnt vmcnt(0)
	v_lshlrev_b32_e32 v9, 16, v2
	v_mul_f32_e32 v9, 0xbfb8aa3b, v9
	v_exp_f32_e32 v9, v9
	v_and_b32_e32 v2, 0xffff0000, v2
	v_mul_f32_e32 v2, 0xbfb8aa3b, v2
	v_exp_f32_e32 v2, v2
	v_add_f32_e32 v9, 1.0, v9
	v_rcp_f32_e32 v42, v9
	v_lshlrev_b32_e32 v9, 16, v3
	v_and_b32_e32 v3, 0xffff0000, v3
	v_add_f32_e32 v2, 1.0, v2
	v_mul_f32_e32 v9, 0xbfb8aa3b, v9
	v_mul_f32_e32 v3, 0xbfb8aa3b, v3
	v_rcp_f32_e32 v43, v2
	v_exp_f32_e32 v9, v9
	v_exp_f32_e32 v3, v3
	v_pk_mul_f32 v[38:39], v[38:39], v[44:45]
	v_pk_mul_f32 v[36:37], v[42:43], v[36:37]
	v_add_f32_e32 v9, 1.0, v9
	v_add_f32_e32 v3, 1.0, v3
	v_cvt_pk_bf16_f32 v2, v36, v37
	v_rcp_f32_e32 v36, v9
	v_rcp_f32_e32 v37, v3
	v_pk_mul_f32 v[42:43], v[136:137], v[8:9] op_sel_hi:[1,0]
	v_pk_mul_f32 v[44:45], v[134:135], v[8:9] op_sel_hi:[1,0]
	v_pk_mul_f32 v[36:37], v[36:37], v[38:39]
	s_nop 0
	v_cvt_pk_bf16_f32 v3, v36, v37
	global_store_dwordx2 v[0:1], v[2:3], off offset:64
	global_load_dwordx4 v[36:39], v[14:15], off offset:192
	s_nop 0
	global_load_dwordx2 v[2:3], v[16:17], off offset:96
	s_waitcnt vmcnt(1)
	v_pk_mul_f32 v[36:37], v[36:37], v[42:43]
	s_waitcnt vmcnt(0)
	v_lshlrev_b32_e32 v9, 16, v2
	v_mul_f32_e32 v9, 0xbfb8aa3b, v9
	v_exp_f32_e32 v9, v9
	v_and_b32_e32 v2, 0xffff0000, v2
	v_mul_f32_e32 v2, 0xbfb8aa3b, v2
	v_exp_f32_e32 v2, v2
	v_add_f32_e32 v9, 1.0, v9
	v_rcp_f32_e32 v42, v9
	v_lshlrev_b32_e32 v9, 16, v3
	v_and_b32_e32 v3, 0xffff0000, v3
	v_add_f32_e32 v2, 1.0, v2
	v_mul_f32_e32 v9, 0xbfb8aa3b, v9
	v_mul_f32_e32 v3, 0xbfb8aa3b, v3
	v_rcp_f32_e32 v43, v2
	v_exp_f32_e32 v9, v9
	v_exp_f32_e32 v3, v3
	v_pk_mul_f32 v[38:39], v[38:39], v[44:45]
	v_pk_mul_f32 v[36:37], v[36:37], v[42:43]
	v_add_f32_e32 v9, 1.0, v9
	v_add_f32_e32 v3, 1.0, v3
	v_cvt_pk_bf16_f32 v2, v36, v37
	v_rcp_f32_e32 v36, v9
	v_rcp_f32_e32 v37, v3
	v_pk_mul_f32 v[42:43], v[132:133], v[8:9] op_sel_hi:[1,0]
	v_pk_mul_f32 v[44:45], v[130:131], v[8:9] op_sel_hi:[1,0]
	v_pk_mul_f32 v[36:37], v[38:39], v[36:37]
	s_nop 0
	v_cvt_pk_bf16_f32 v3, v36, v37
	global_store_dwordx2 v[0:1], v[2:3], off offset:96
	global_load_dwordx4 v[36:39], v[14:15], off offset:256
	s_nop 0
	global_load_dwordx2 v[2:3], v[16:17], off offset:128
	s_waitcnt vmcnt(1)
	v_pk_mul_f32 v[36:37], v[36:37], v[42:43]
	s_waitcnt vmcnt(0)
	v_lshlrev_b32_e32 v9, 16, v2
	v_mul_f32_e32 v9, 0xbfb8aa3b, v9
	v_exp_f32_e32 v9, v9
	v_and_b32_e32 v2, 0xffff0000, v2
	v_mul_f32_e32 v2, 0xbfb8aa3b, v2
	v_exp_f32_e32 v2, v2
	v_add_f32_e32 v9, 1.0, v9
	v_rcp_f32_e32 v42, v9
	v_lshlrev_b32_e32 v9, 16, v3
	v_and_b32_e32 v3, 0xffff0000, v3
	v_add_f32_e32 v2, 1.0, v2
	v_mul_f32_e32 v9, 0xbfb8aa3b, v9
	v_mul_f32_e32 v3, 0xbfb8aa3b, v3
	v_rcp_f32_e32 v43, v2
	v_exp_f32_e32 v9, v9
	v_exp_f32_e32 v3, v3
	v_pk_mul_f32 v[38:39], v[38:39], v[44:45]
	v_pk_mul_f32 v[36:37], v[36:37], v[42:43]
	v_add_f32_e32 v9, 1.0, v9
	v_add_f32_e32 v3, 1.0, v3
	v_cvt_pk_bf16_f32 v2, v36, v37
	v_rcp_f32_e32 v36, v9
	v_rcp_f32_e32 v37, v3
	v_pk_mul_f32 v[42:43], v[128:129], v[8:9] op_sel_hi:[1,0]
	v_pk_mul_f32 v[44:45], v[126:127], v[8:9] op_sel_hi:[1,0]
	v_pk_mul_f32 v[36:37], v[38:39], v[36:37]
	s_nop 0
	v_cvt_pk_bf16_f32 v3, v36, v37
	global_store_dwordx2 v[0:1], v[2:3], off offset:128
	global_load_dwordx4 v[36:39], v[14:15], off offset:320
	s_nop 0
	global_load_dwordx2 v[2:3], v[16:17], off offset:160
	s_waitcnt vmcnt(1)
	v_pk_mul_f32 v[36:37], v[36:37], v[42:43]
	s_waitcnt vmcnt(0)
	v_lshlrev_b32_e32 v9, 16, v2
	v_mul_f32_e32 v9, 0xbfb8aa3b, v9
	v_exp_f32_e32 v9, v9
	v_and_b32_e32 v2, 0xffff0000, v2
	v_mul_f32_e32 v2, 0xbfb8aa3b, v2
	v_exp_f32_e32 v2, v2
	v_add_f32_e32 v9, 1.0, v9
	v_rcp_f32_e32 v42, v9
	v_lshlrev_b32_e32 v9, 16, v3
	v_and_b32_e32 v3, 0xffff0000, v3
	v_add_f32_e32 v2, 1.0, v2
	v_mul_f32_e32 v9, 0xbfb8aa3b, v9
	v_mul_f32_e32 v3, 0xbfb8aa3b, v3
	v_rcp_f32_e32 v43, v2
	v_exp_f32_e32 v9, v9
	v_exp_f32_e32 v3, v3
	v_pk_mul_f32 v[38:39], v[38:39], v[44:45]
	v_pk_mul_f32 v[36:37], v[36:37], v[42:43]
	v_add_f32_e32 v9, 1.0, v9
	v_add_f32_e32 v3, 1.0, v3
	v_cvt_pk_bf16_f32 v2, v36, v37
	v_rcp_f32_e32 v36, v9
	v_rcp_f32_e32 v37, v3
	v_pk_mul_f32 v[42:43], v[124:125], v[8:9] op_sel_hi:[1,0]
	v_pk_mul_f32 v[44:45], v[122:123], v[8:9] op_sel_hi:[1,0]
	v_pk_mul_f32 v[36:37], v[38:39], v[36:37]
	s_nop 0
	v_cvt_pk_bf16_f32 v3, v36, v37
	global_store_dwordx2 v[0:1], v[2:3], off offset:160
	global_load_dwordx4 v[36:39], v[14:15], off offset:384
	s_nop 0
	global_load_dwordx2 v[2:3], v[16:17], off offset:192
	s_waitcnt vmcnt(1)
	v_pk_mul_f32 v[36:37], v[42:43], v[36:37]
	s_waitcnt vmcnt(0)
	v_lshlrev_b32_e32 v9, 16, v2
	v_mul_f32_e32 v9, 0xbfb8aa3b, v9
	v_exp_f32_e32 v9, v9
	v_and_b32_e32 v2, 0xffff0000, v2
	v_mul_f32_e32 v2, 0xbfb8aa3b, v2
	v_exp_f32_e32 v2, v2
	v_add_f32_e32 v9, 1.0, v9
	v_rcp_f32_e32 v42, v9
	v_lshlrev_b32_e32 v9, 16, v3
	v_and_b32_e32 v3, 0xffff0000, v3
	v_add_f32_e32 v2, 1.0, v2
	v_mul_f32_e32 v9, 0xbfb8aa3b, v9
	v_mul_f32_e32 v3, 0xbfb8aa3b, v3
	v_rcp_f32_e32 v43, v2
	v_exp_f32_e32 v9, v9
	v_exp_f32_e32 v3, v3
	v_pk_mul_f32 v[38:39], v[44:45], v[38:39]
	v_pk_mul_f32 v[36:37], v[36:37], v[42:43]
	v_add_f32_e32 v9, 1.0, v9
	v_add_f32_e32 v3, 1.0, v3
	v_cvt_pk_bf16_f32 v2, v36, v37
	v_rcp_f32_e32 v36, v9
	v_rcp_f32_e32 v37, v3
	v_pk_mul_f32 v[42:43], v[120:121], v[8:9] op_sel_hi:[1,0]
	v_pk_mul_f32 v[44:45], v[118:119], v[8:9] op_sel_hi:[1,0]
	v_pk_mul_f32 v[36:37], v[38:39], v[36:37]
	s_nop 0
	v_cvt_pk_bf16_f32 v3, v36, v37
	global_store_dwordx2 v[0:1], v[2:3], off offset:192
	global_load_dwordx4 v[36:39], v[14:15], off offset:448
	s_nop 0
	global_load_dwordx2 v[2:3], v[16:17], off offset:224
	s_waitcnt vmcnt(1)
	v_pk_mul_f32 v[36:37], v[42:43], v[36:37]
	s_waitcnt vmcnt(0)
	v_lshlrev_b32_e32 v9, 16, v2
	v_mul_f32_e32 v9, 0xbfb8aa3b, v9
	v_exp_f32_e32 v9, v9
	v_and_b32_e32 v2, 0xffff0000, v2
	v_mul_f32_e32 v2, 0xbfb8aa3b, v2
	v_exp_f32_e32 v2, v2
	v_add_f32_e32 v9, 1.0, v9
	v_rcp_f32_e32 v42, v9
	v_lshlrev_b32_e32 v9, 16, v3
	v_and_b32_e32 v3, 0xffff0000, v3
	v_add_f32_e32 v2, 1.0, v2
	v_mul_f32_e32 v9, 0xbfb8aa3b, v9
	v_mul_f32_e32 v3, 0xbfb8aa3b, v3
	v_rcp_f32_e32 v43, v2
	v_exp_f32_e32 v9, v9
	v_exp_f32_e32 v3, v3
	v_pk_mul_f32 v[38:39], v[44:45], v[38:39]
	v_pk_mul_f32 v[36:37], v[36:37], v[42:43]
	v_add_f32_e32 v9, 1.0, v9
	v_add_f32_e32 v3, 1.0, v3
	v_cvt_pk_bf16_f32 v2, v36, v37
	v_rcp_f32_e32 v36, v9
	v_rcp_f32_e32 v37, v3
	v_pk_mul_f32 v[42:43], v[116:117], v[8:9] op_sel_hi:[1,0]
	v_pk_mul_f32 v[44:45], v[114:115], v[8:9] op_sel_hi:[1,0]
	v_pk_mul_f32 v[36:37], v[38:39], v[36:37]
	s_nop 0
	v_cvt_pk_bf16_f32 v3, v36, v37
	global_store_dwordx2 v[0:1], v[2:3], off offset:224
	global_load_dwordx4 v[36:39], v[14:15], off offset:512
	s_nop 0
	global_load_dwordx2 v[2:3], v[16:17], off offset:256
	s_waitcnt vmcnt(1)
	v_pk_mul_f32 v[36:37], v[42:43], v[36:37]
	s_waitcnt vmcnt(0)
	v_lshlrev_b32_e32 v9, 16, v2
	v_mul_f32_e32 v9, 0xbfb8aa3b, v9
	v_exp_f32_e32 v9, v9
	v_and_b32_e32 v2, 0xffff0000, v2
	v_mul_f32_e32 v2, 0xbfb8aa3b, v2
	v_exp_f32_e32 v2, v2
	v_add_f32_e32 v9, 1.0, v9
	v_rcp_f32_e32 v42, v9
	v_lshlrev_b32_e32 v9, 16, v3
	v_and_b32_e32 v3, 0xffff0000, v3
	v_add_f32_e32 v2, 1.0, v2
	v_mul_f32_e32 v9, 0xbfb8aa3b, v9
	v_mul_f32_e32 v3, 0xbfb8aa3b, v3
	v_rcp_f32_e32 v43, v2
	v_exp_f32_e32 v9, v9
	v_exp_f32_e32 v3, v3
	v_pk_mul_f32 v[38:39], v[44:45], v[38:39]
	v_pk_mul_f32 v[36:37], v[36:37], v[42:43]
	v_add_f32_e32 v9, 1.0, v9
	v_add_f32_e32 v3, 1.0, v3
	v_cvt_pk_bf16_f32 v2, v36, v37
	v_rcp_f32_e32 v36, v9
	v_rcp_f32_e32 v37, v3
	v_pk_mul_f32 v[40:41], v[40:41], v[8:9] op_sel_hi:[1,0]
	v_pk_mul_f32 v[34:35], v[34:35], v[8:9] op_sel_hi:[1,0]
	v_pk_mul_f32 v[36:37], v[38:39], v[36:37]
	s_nop 0
	v_cvt_pk_bf16_f32 v3, v36, v37
	global_store_dwordx2 v[0:1], v[2:3], off offset:256
	global_load_dwordx4 v[36:39], v[14:15], off offset:576
	s_nop 0
	global_load_dwordx2 v[2:3], v[16:17], off offset:288
	s_waitcnt vmcnt(1)
	v_pk_mul_f32 v[34:35], v[34:35], v[38:39]
	s_waitcnt vmcnt(0)
	v_lshlrev_b32_e32 v9, 16, v2
	v_mul_f32_e32 v9, 0xbfb8aa3b, v9
	v_exp_f32_e32 v9, v9
	v_and_b32_e32 v2, 0xffff0000, v2
	v_mul_f32_e32 v2, 0xbfb8aa3b, v2
	v_exp_f32_e32 v2, v2
	v_add_f32_e32 v9, 1.0, v9
	v_rcp_f32_e32 v38, v9
	v_lshlrev_b32_e32 v9, 16, v3
	v_and_b32_e32 v3, 0xffff0000, v3
	v_add_f32_e32 v2, 1.0, v2
	v_mul_f32_e32 v9, 0xbfb8aa3b, v9
	v_mul_f32_e32 v3, 0xbfb8aa3b, v3
	v_rcp_f32_e32 v39, v2
	v_exp_f32_e32 v9, v9
	v_exp_f32_e32 v3, v3
	v_pk_mul_f32 v[36:37], v[40:41], v[36:37]
	v_add_f32_e32 v9, 1.0, v9
	v_pk_mul_f32 v[36:37], v[36:37], v[38:39]
	v_add_f32_e32 v3, 1.0, v3
	v_cvt_pk_bf16_f32 v2, v36, v37
	v_rcp_f32_e32 v36, v9
	v_rcp_f32_e32 v37, v3
	v_pk_mul_f32 v[32:33], v[32:33], v[8:9] op_sel_hi:[1,0]
	v_pk_mul_f32 v[30:31], v[30:31], v[8:9] op_sel_hi:[1,0]
	v_pk_mul_f32 v[34:35], v[34:35], v[36:37]
	s_nop 0
	v_cvt_pk_bf16_f32 v3, v34, v35
	global_store_dwordx2 v[0:1], v[2:3], off offset:288
	global_load_dwordx4 v[34:37], v[14:15], off offset:640
	s_nop 0
	global_load_dwordx2 v[2:3], v[16:17], off offset:320
	s_waitcnt vmcnt(1)
	v_pk_mul_f32 v[32:33], v[32:33], v[34:35]
	s_waitcnt vmcnt(0)
	v_lshlrev_b32_e32 v9, 16, v2
	v_mul_f32_e32 v9, 0xbfb8aa3b, v9
	v_exp_f32_e32 v9, v9
	v_and_b32_e32 v2, 0xffff0000, v2
	v_mul_f32_e32 v2, 0xbfb8aa3b, v2
	v_exp_f32_e32 v2, v2
	v_add_f32_e32 v9, 1.0, v9
	v_rcp_f32_e32 v34, v9
	v_lshlrev_b32_e32 v9, 16, v3
	v_and_b32_e32 v3, 0xffff0000, v3
	v_add_f32_e32 v2, 1.0, v2
	v_mul_f32_e32 v9, 0xbfb8aa3b, v9
	v_mul_f32_e32 v3, 0xbfb8aa3b, v3
	v_rcp_f32_e32 v35, v2
	v_exp_f32_e32 v9, v9
	v_exp_f32_e32 v3, v3
	v_pk_mul_f32 v[30:31], v[30:31], v[36:37]
	v_pk_mul_f32 v[32:33], v[32:33], v[34:35]
	v_add_f32_e32 v9, 1.0, v9
	v_add_f32_e32 v3, 1.0, v3
	v_cvt_pk_bf16_f32 v2, v32, v33
	v_rcp_f32_e32 v32, v9
	v_rcp_f32_e32 v33, v3
	v_pk_mul_f32 v[28:29], v[28:29], v[8:9] op_sel_hi:[1,0]
	v_pk_mul_f32 v[26:27], v[26:27], v[8:9] op_sel_hi:[1,0]
	v_pk_mul_f32 v[30:31], v[30:31], v[32:33]
	s_nop 0
	v_cvt_pk_bf16_f32 v3, v30, v31
	global_store_dwordx2 v[0:1], v[2:3], off offset:320
	global_load_dwordx4 v[30:33], v[14:15], off offset:704
	s_nop 0
	global_load_dwordx2 v[2:3], v[16:17], off offset:352
	s_waitcnt vmcnt(1)
	v_pk_mul_f32 v[28:29], v[28:29], v[30:31]
	s_waitcnt vmcnt(0)
	v_lshlrev_b32_e32 v9, 16, v2
	v_mul_f32_e32 v9, 0xbfb8aa3b, v9
	v_exp_f32_e32 v9, v9
	v_and_b32_e32 v2, 0xffff0000, v2
	v_mul_f32_e32 v2, 0xbfb8aa3b, v2
	v_exp_f32_e32 v2, v2
	v_add_f32_e32 v9, 1.0, v9
	v_rcp_f32_e32 v30, v9
	v_lshlrev_b32_e32 v9, 16, v3
	v_and_b32_e32 v3, 0xffff0000, v3
	v_add_f32_e32 v2, 1.0, v2
	v_mul_f32_e32 v9, 0xbfb8aa3b, v9
	v_mul_f32_e32 v3, 0xbfb8aa3b, v3
	v_rcp_f32_e32 v31, v2
	v_exp_f32_e32 v9, v9
	v_exp_f32_e32 v3, v3
	v_pk_mul_f32 v[26:27], v[26:27], v[32:33]
	v_pk_mul_f32 v[28:29], v[28:29], v[30:31]
	v_add_f32_e32 v9, 1.0, v9
	v_add_f32_e32 v3, 1.0, v3
	v_cvt_pk_bf16_f32 v2, v28, v29
	v_rcp_f32_e32 v28, v9
	v_rcp_f32_e32 v29, v3
	v_pk_mul_f32 v[24:25], v[24:25], v[8:9] op_sel_hi:[1,0]
	v_pk_mul_f32 v[22:23], v[22:23], v[8:9] op_sel_hi:[1,0]
	v_pk_mul_f32 v[26:27], v[26:27], v[28:29]
	s_nop 0
	v_cvt_pk_bf16_f32 v3, v26, v27
	global_store_dwordx2 v[0:1], v[2:3], off offset:352
	global_load_dwordx4 v[26:29], v[14:15], off offset:768
	s_nop 0
	global_load_dwordx2 v[2:3], v[16:17], off offset:384
	s_waitcnt vmcnt(1)
	v_pk_mul_f32 v[24:25], v[24:25], v[26:27]
	s_waitcnt vmcnt(0)
	v_lshlrev_b32_e32 v9, 16, v2
	v_mul_f32_e32 v9, 0xbfb8aa3b, v9
	v_exp_f32_e32 v9, v9
	v_and_b32_e32 v2, 0xffff0000, v2
	v_mul_f32_e32 v2, 0xbfb8aa3b, v2
	v_exp_f32_e32 v2, v2
	v_add_f32_e32 v9, 1.0, v9
	v_rcp_f32_e32 v26, v9
	v_lshlrev_b32_e32 v9, 16, v3
	v_and_b32_e32 v3, 0xffff0000, v3
	v_add_f32_e32 v2, 1.0, v2
	v_mul_f32_e32 v9, 0xbfb8aa3b, v9
	v_mul_f32_e32 v3, 0xbfb8aa3b, v3
	v_rcp_f32_e32 v27, v2
	v_exp_f32_e32 v9, v9
	v_exp_f32_e32 v3, v3
	v_pk_mul_f32 v[22:23], v[22:23], v[28:29]
	v_pk_mul_f32 v[24:25], v[24:25], v[26:27]
	v_add_f32_e32 v9, 1.0, v9
	v_add_f32_e32 v3, 1.0, v3
	v_cvt_pk_bf16_f32 v2, v24, v25
	v_rcp_f32_e32 v24, v9
	v_rcp_f32_e32 v25, v3
	v_pk_mul_f32 v[20:21], v[20:21], v[8:9] op_sel_hi:[1,0]
	v_pk_mul_f32 v[18:19], v[18:19], v[8:9] op_sel_hi:[1,0]
	v_pk_mul_f32 v[22:23], v[22:23], v[24:25]
	s_nop 0
	v_cvt_pk_bf16_f32 v3, v22, v23
	global_store_dwordx2 v[0:1], v[2:3], off offset:384
	global_load_dwordx4 v[22:25], v[14:15], off offset:832
	s_nop 0
	global_load_dwordx2 v[2:3], v[16:17], off offset:416
	s_waitcnt vmcnt(1)
	v_pk_mul_f32 v[20:21], v[20:21], v[22:23]
	s_waitcnt vmcnt(0)
	v_lshlrev_b32_e32 v9, 16, v2
	v_mul_f32_e32 v9, 0xbfb8aa3b, v9
	v_exp_f32_e32 v9, v9
	v_and_b32_e32 v2, 0xffff0000, v2
	v_mul_f32_e32 v2, 0xbfb8aa3b, v2
	v_exp_f32_e32 v2, v2
	v_add_f32_e32 v9, 1.0, v9
	v_rcp_f32_e32 v22, v9
	v_lshlrev_b32_e32 v9, 16, v3
	v_and_b32_e32 v3, 0xffff0000, v3
	v_add_f32_e32 v2, 1.0, v2
	v_mul_f32_e32 v9, 0xbfb8aa3b, v9
	v_mul_f32_e32 v3, 0xbfb8aa3b, v3
	v_rcp_f32_e32 v23, v2
	v_exp_f32_e32 v9, v9
	v_exp_f32_e32 v3, v3
	v_pk_mul_f32 v[18:19], v[18:19], v[24:25]
	v_pk_mul_f32 v[20:21], v[20:21], v[22:23]
	v_add_f32_e32 v9, 1.0, v9
	v_add_f32_e32 v3, 1.0, v3
	v_cvt_pk_bf16_f32 v2, v20, v21
	v_rcp_f32_e32 v20, v9
	v_rcp_f32_e32 v21, v3
	v_pk_mul_f32 v[12:13], v[12:13], v[8:9] op_sel_hi:[1,0]
	v_pk_mul_f32 v[10:11], v[10:11], v[8:9] op_sel_hi:[1,0]
	v_pk_mul_f32 v[18:19], v[18:19], v[20:21]
	s_nop 0
	v_cvt_pk_bf16_f32 v3, v18, v19
	global_store_dwordx2 v[0:1], v[2:3], off offset:416
	global_load_dwordx4 v[18:21], v[14:15], off offset:896
	s_nop 0
	global_load_dwordx2 v[2:3], v[16:17], off offset:448
	s_waitcnt vmcnt(1)
	v_pk_mul_f32 v[12:13], v[12:13], v[18:19]
	s_waitcnt vmcnt(0)
	v_lshlrev_b32_e32 v9, 16, v2
	v_mul_f32_e32 v9, 0xbfb8aa3b, v9
	v_exp_f32_e32 v9, v9
	v_and_b32_e32 v2, 0xffff0000, v2
	v_mul_f32_e32 v2, 0xbfb8aa3b, v2
	v_exp_f32_e32 v2, v2
	v_add_f32_e32 v9, 1.0, v9
	v_rcp_f32_e32 v18, v9
	v_lshlrev_b32_e32 v9, 16, v3
	v_and_b32_e32 v3, 0xffff0000, v3
	v_add_f32_e32 v2, 1.0, v2
	v_mul_f32_e32 v9, 0xbfb8aa3b, v9
	v_mul_f32_e32 v3, 0xbfb8aa3b, v3
	v_rcp_f32_e32 v19, v2
	v_exp_f32_e32 v9, v9
	v_exp_f32_e32 v3, v3
	v_pk_mul_f32 v[10:11], v[10:11], v[20:21]
	v_pk_mul_f32 v[12:13], v[12:13], v[18:19]
	v_add_f32_e32 v9, 1.0, v9
	v_add_f32_e32 v3, 1.0, v3
	v_cvt_pk_bf16_f32 v2, v12, v13
	v_rcp_f32_e32 v12, v9
	v_rcp_f32_e32 v13, v3
	v_pk_mul_f32 v[6:7], v[6:7], v[8:9] op_sel_hi:[1,0]
	v_pk_mul_f32 v[4:5], v[4:5], v[8:9] op_sel_hi:[1,0]
	v_pk_mul_f32 v[10:11], v[10:11], v[12:13]
	s_nop 0
	v_cvt_pk_bf16_f32 v3, v10, v11
	global_store_dwordx2 v[0:1], v[2:3], off offset:448
	global_load_dwordx4 v[10:13], v[14:15], off offset:960
	s_nop 0
	global_load_dwordx2 v[2:3], v[16:17], off offset:480
	s_waitcnt vmcnt(1)
	v_pk_mul_f32 v[6:7], v[6:7], v[10:11]
	s_waitcnt vmcnt(0)
	v_lshlrev_b32_e32 v8, 16, v2
	v_and_b32_e32 v2, 0xffff0000, v2
	v_mul_f32_e32 v8, 0xbfb8aa3b, v8
	v_mul_f32_e32 v2, 0xbfb8aa3b, v2
	v_exp_f32_e32 v8, v8
	v_exp_f32_e32 v2, v2
	v_pk_mul_f32 v[4:5], v[4:5], v[12:13]
	v_add_f32_e32 v8, 1.0, v8
	v_add_f32_e32 v2, 1.0, v2
	v_rcp_f32_e32 v8, v8
	v_rcp_f32_e32 v9, v2
	s_nop 0
	v_pk_mul_f32 v[6:7], v[6:7], v[8:9]
	s_nop 0
	v_cvt_pk_bf16_f32 v2, v6, v7
	v_lshlrev_b32_e32 v6, 16, v3
	v_and_b32_e32 v3, 0xffff0000, v3
	v_mul_f32_e32 v6, 0xbfb8aa3b, v6
	v_mul_f32_e32 v3, 0xbfb8aa3b, v3
	v_exp_f32_e32 v6, v6
	v_exp_f32_e32 v3, v3
	v_add_f32_e32 v6, 1.0, v6
	v_add_f32_e32 v3, 1.0, v3
	v_rcp_f32_e32 v6, v6
	v_rcp_f32_e32 v7, v3
	s_nop 0
	v_pk_mul_f32 v[4:5], v[4:5], v[6:7]
	s_nop 0
	v_cvt_pk_bf16_f32 v3, v4, v5
	global_store_dwordx2 v[0:1], v[2:3], off offset:480
	s_barrier
	s_cbranch_scc0 .LBB0_667
